# best with the P3->P4 barrier as a 4-workgroup group barrier
# speedup vs baseline: 1.0058x; 1.0026x over previous
.LBB0_434:
	s_cmp_gt_i32 s83, 4
	s_cselect_b64 s[0:1], -1, 0
	s_and_b64 s[4:5], s[6:7], s[0:1]
	s_andn2_b64 vcc, exec, s[4:5]
	s_cbranch_vccnz .LBB0_488
	s_waitcnt vmcnt(0)
	s_waitcnt vmcnt(0)
	s_barrier
	s_and_saveexec_b64 s[4:5], s[94:95]
	s_cbranch_execz .LBB0_487
	s_add_u32 s6, s80, 0x2380000
	s_addc_u32 s7, s81, 0
	s_and_b32 s8, s2, 63
	s_lshl_b32 s8, s8, 2
	v_mov_b32_e32 v4, s8
	v_mov_b32_e32 v5, 1
	global_atomic_add v6, v4, v5, s[6:7] sc0
	buffer_inv sc1
	s_waitcnt vmcnt(0)
	v_readfirstlane_b32 s10, v6
	s_cmp_lg_u32 s10, 3
	s_cbranch_scc1 .Lgrp_w_3
	global_atomic_add v4, v5, s[6:7] offset:256
	s_branch .Lgrp_d_3

.Lgrp_w2_3:
	global_load_dword v6, v4, s[6:7] offset:256 sc1
	s_waitcnt vmcnt(0)
	v_readfirstlane_b32 s11, v6
	s_cmp_ge_u32 s11, 1
	s_cbranch_scc1 .Lgrp_d_3
	s_sleep 1
	s_add_i32 s10, s10, 1
	s_cmp_lt_u32 s10, 0x100000
	s_cbranch_scc1 .Lgrp_w2_3

.LBB0_529:
	s_cmp_gt_i32 s83, 5
	s_cselect_b64 s[0:1], -1, 0
	s_and_b64 s[4:5], s[16:17], s[0:1]
	s_andn2_b64 vcc, exec, s[4:5]
	s_cbranch_vccnz .LBB0_583
	s_waitcnt vmcnt(0)
	s_waitcnt vmcnt(0) lgkmcnt(0)
	s_barrier
	s_and_saveexec_b64 s[4:5], s[94:95]
	s_cbranch_execz .LBB0_582
	v_mov_b32_e32 v1, 0x23ff0
	ds_read_b32 v2, v1
	ds_read_b32 v3, v1 offset:4
	s_add_u32 s6, s80, 0x2380000
	s_addc_u32 s7, s81, 0
	s_lshl_b32 s8, s87, 8
	s_add_i32 s9, s8, 0x1400
	s_add_i32 s8, s8, 0x2400
	v_mov_b32_e32 v4, s9
	v_mov_b32_e32 v5, 1
	global_atomic_add v6, v4, v5, s[6:7] sc0
	buffer_inv sc1
	s_waitcnt vmcnt(0) lgkmcnt(0)
	v_readfirstlane_b32 s10, v6
	v_readfirstlane_b32 s11, v2
	v_readfirstlane_b32 s16, v3
	s_add_i32 s10, s10, 1
	s_mul_i32 s11, s11, 4
	s_cmp_lg_u32 s10, s11
	s_cbranch_scc1 .Lxb_nl_4
	v_mov_b32_e32 v4, 0x3400
	global_atomic_add v6, v4, v5, s[6:7] sc0
	s_waitcnt vmcnt(0)
	v_readfirstlane_b32 s10, v6
	s_add_i32 s10, s10, 1
	s_mul_i32 s16, s16, 4
	s_cmp_lg_u32 s10, s16
	s_cbranch_scc1 .Lxb_nl_4
	v_mov_b32_e32 v4, 0x2400
	global_atomic_add v4, v5, s[6:7]
	global_atomic_add v4, v5, s[6:7] offset:256
	global_atomic_add v4, v5, s[6:7] offset:512
	global_atomic_add v4, v5, s[6:7] offset:768
	global_atomic_add v4, v5, s[6:7] offset:1024
	global_atomic_add v4, v5, s[6:7] offset:1280
	global_atomic_add v4, v5, s[6:7] offset:1536
	global_atomic_add v4, v5, s[6:7] offset:1792
	global_atomic_add v4, v5, s[6:7] offset:2048
	global_atomic_add v4, v5, s[6:7] offset:2304
	global_atomic_add v4, v5, s[6:7] offset:2560
	global_atomic_add v4, v5, s[6:7] offset:2816
	global_atomic_add v4, v5, s[6:7] offset:3072
	global_atomic_add v4, v5, s[6:7] offset:3328
	global_atomic_add v4, v5, s[6:7] offset:3584
	global_atomic_add v4, v5, s[6:7] offset:3840
	s_branch .Lxb_done_4

.LBB0_612:
	s_cmp_gt_i32 s83, 6
	s_cselect_b64 s[0:1], -1, 0
	s_and_b64 s[4:5], s[6:7], s[0:1]
	s_andn2_b64 vcc, exec, s[4:5]
	s_cbranch_vccnz .LBB0_666
	s_waitcnt vmcnt(0)
	s_waitcnt vmcnt(0) lgkmcnt(0)
	s_barrier
	s_and_saveexec_b64 s[4:5], s[94:95]
	s_cbranch_execz .LBB0_665
	v_mov_b32_e32 v1, 0x23ff0
	ds_read_b32 v2, v1
	ds_read_b32 v3, v1 offset:4
	s_add_u32 s6, s80, 0x2380000
	s_addc_u32 s7, s81, 0
	s_lshl_b32 s8, s87, 8
	s_add_i32 s9, s8, 0x1400
	s_add_i32 s8, s8, 0x2400
	v_mov_b32_e32 v4, s9
	v_mov_b32_e32 v5, 1
	global_atomic_add v6, v4, v5, s[6:7] sc0
	buffer_inv sc1
	s_waitcnt vmcnt(0) lgkmcnt(0)
	v_readfirstlane_b32 s10, v6
	v_readfirstlane_b32 s11, v2
	v_readfirstlane_b32 s16, v3
	s_add_i32 s10, s10, 1
	s_mul_i32 s11, s11, 5
	s_cmp_lg_u32 s10, s11
	s_cbranch_scc1 .Lxb_nl_5
	v_mov_b32_e32 v4, 0x3400
	global_atomic_add v6, v4, v5, s[6:7] sc0
	s_waitcnt vmcnt(0)
	v_readfirstlane_b32 s10, v6
	s_add_i32 s10, s10, 1
	s_mul_i32 s16, s16, 5
	s_cmp_lg_u32 s10, s16
	s_cbranch_scc1 .Lxb_nl_5
	v_mov_b32_e32 v4, 0x2400
	global_atomic_add v4, v5, s[6:7]
	global_atomic_add v4, v5, s[6:7] offset:256
	global_atomic_add v4, v5, s[6:7] offset:512
	global_atomic_add v4, v5, s[6:7] offset:768
	global_atomic_add v4, v5, s[6:7] offset:1024
	global_atomic_add v4, v5, s[6:7] offset:1280
	global_atomic_add v4, v5, s[6:7] offset:1536
	global_atomic_add v4, v5, s[6:7] offset:1792
	global_atomic_add v4, v5, s[6:7] offset:2048
	global_atomic_add v4, v5, s[6:7] offset:2304
	global_atomic_add v4, v5, s[6:7] offset:2560
	global_atomic_add v4, v5, s[6:7] offset:2816
	global_atomic_add v4, v5, s[6:7] offset:3072
	global_atomic_add v4, v5, s[6:7] offset:3328
	global_atomic_add v4, v5, s[6:7] offset:3584
	global_atomic_add v4, v5, s[6:7] offset:3840
	s_branch .Lxb_done_5
